# group-norm (post-scan) loop: the 12 loads of an iteration issued together as global loads with counted waits
# speedup vs baseline: 1.0448x; 1.0040x over previous
.LBB0_140:
	v_lshl_add_u64 v[26:27], v[16:17], 0, s[8:9]
	v_lshl_add_u64 v[30:31], v[4:5], 0, s[8:9]
	v_lshl_add_u64 v[32:33], v[2:3], 0, s[8:9]
	v_lshl_add_u64 v[34:35], v[20:21], 0, s[8:9]
	v_lshl_add_u64 v[36:37], v[22:23], 0, s[8:9]
	global_load_dwordx4 v[46:49], v[26:27], off
	global_load_dwordx4 v[50:53], v[26:27], off offset:1024
	global_load_dwordx4 v[54:57], v[30:31], off
	global_load_dwordx4 v[58:61], v[32:33], off
	global_load_dword v62, v[24:25], off
	global_load_dwordx4 v[64:67], v[34:35], off
	global_load_dwordx4 v[68:71], v[36:37], off
	global_load_dwordx4 v[72:75], v[30:31], off offset:1024
	global_load_dwordx4 v[76:79], v[32:33], off offset:1024
	global_load_dword v98, v[24:25], off offset:16
	global_load_dwordx4 v[80:83], v[34:35], off offset:1024
	global_load_dwordx4 v[84:87], v[36:37], off offset:1024
	v_lshl_add_u64 v[24:25], v[24:25], 0, 32
	s_waitcnt vmcnt(11)
	v_add_f32_e32 v1, v46, v47
	v_add_f32_e32 v1, v48, v1
	v_add_f32_e32 v1, v49, v1
	s_nop 1
	v_add_f32_dpp v1, v1, v1 quad_perm:[1,0,3,2] row_mask:0xf bank_mask:0xf bound_ctrl:1
	s_nop 1
	v_add_f32_dpp v1, v1, v1 quad_perm:[2,3,0,1] row_mask:0xf bank_mask:0xf bound_ctrl:1
	s_nop 1
	v_add_f32_dpp v1, v1, v1 row_half_mirror row_mask:0xf bank_mask:0xf bound_ctrl:1
	s_nop 1
	v_add_f32_dpp v1, v1, v1 row_mirror row_mask:0xf bank_mask:0xf bound_ctrl:1
	v_fmamk_f32 v47, v1, 0xbc800000, v47
	v_fmamk_f32 v46, v1, 0xbc800000, v46
	v_fmamk_f32 v49, v1, 0xbc800000, v49
	v_fmac_f32_e32 v48, 0xbc800000, v1
	v_pk_mul_f32 v[88:89], v[46:47], v[46:47]
	v_pk_mul_f32 v[90:91], v[48:49], v[48:49]
	v_add_f32_e32 v1, v88, v89
	v_add_f32_e32 v1, v90, v1
	v_add_f32_e32 v1, v91, v1
	s_nop 1
	v_add_f32_dpp v1, v1, v1 quad_perm:[1,0,3,2] row_mask:0xf bank_mask:0xf bound_ctrl:1
	s_nop 1
	v_add_f32_dpp v1, v1, v1 quad_perm:[2,3,0,1] row_mask:0xf bank_mask:0xf bound_ctrl:1
	s_nop 1
	v_add_f32_dpp v1, v1, v1 row_half_mirror row_mask:0xf bank_mask:0xf bound_ctrl:1
	s_nop 1
	v_add_f32_dpp v1, v1, v1 row_mirror row_mask:0xf bank_mask:0xf bound_ctrl:1
	v_fmamk_f32 v1, v1, 0x3c800000, v197
	v_cmp_gt_f32_e32 vcc, s81, v1
	v_mul_f32_e32 v29, 0x4b800000, v1
	s_nop 0
	v_cndmask_b32_e32 v1, v1, v29, vcc
	v_rsq_f32_e32 v1, v1
	s_nop 0
	v_mul_f32_e32 v29, 0x45800000, v1
	v_cndmask_b32_e32 v92, v1, v29, vcc
	v_pk_mul_f32 v[94:95], v[46:47], v[92:93] op_sel_hi:[1,0]
	v_pk_mul_f32 v[96:97], v[48:49], v[92:93] op_sel_hi:[1,0]
	s_waitcnt vmcnt(8)
	v_pk_fma_f32 v[94:95], v[54:55], v[94:95], v[58:59]
	v_pk_fma_f32 v[96:97], v[56:57], v[96:97], v[60:61]
	s_waitcnt vmcnt(6)
	v_pk_fma_f32 v[94:95], v[64:65], v[62:63], v[94:95] op_sel_hi:[1,0,1]
	v_pk_fma_f32 v[96:97], v[66:67], v[62:63], v[96:97] op_sel_hi:[1,0,1]
	s_waitcnt vmcnt(5)
	v_pk_mul_f32 v[94:95], v[68:69], v[94:95]
	v_pk_mul_f32 v[96:97], v[70:71], v[96:97]
	v_cvt_pk_bf16_f32 v94, v94, v95
	s_nop 0
	v_cvt_pk_bf16_f32 v95, v96, v97
	global_store_dwordx2 v[18:19], v[94:95], off
	s_waitcnt vmcnt(10)
	v_add_f32_e32 v1, v50, v51
	v_add_f32_e32 v1, v52, v1
	v_add_f32_e32 v1, v53, v1
	s_nop 1
	v_add_f32_dpp v1, v1, v1 quad_perm:[1,0,3,2] row_mask:0xf bank_mask:0xf bound_ctrl:1
	s_nop 1
	v_add_f32_dpp v1, v1, v1 quad_perm:[2,3,0,1] row_mask:0xf bank_mask:0xf bound_ctrl:1
	s_nop 1
	v_add_f32_dpp v1, v1, v1 row_half_mirror row_mask:0xf bank_mask:0xf bound_ctrl:1
	s_nop 1
	v_add_f32_dpp v1, v1, v1 row_mirror row_mask:0xf bank_mask:0xf bound_ctrl:1
	v_fmamk_f32 v51, v1, 0xbc800000, v51
	v_fmamk_f32 v50, v1, 0xbc800000, v50
	v_fmamk_f32 v53, v1, 0xbc800000, v53
	v_fmac_f32_e32 v52, 0xbc800000, v1
	v_pk_mul_f32 v[88:89], v[50:51], v[50:51]
	v_pk_mul_f32 v[90:91], v[52:53], v[52:53]
	v_add_f32_e32 v1, v88, v89
	v_add_f32_e32 v1, v90, v1
	v_add_f32_e32 v1, v91, v1
	s_nop 1
	v_add_f32_dpp v1, v1, v1 quad_perm:[1,0,3,2] row_mask:0xf bank_mask:0xf bound_ctrl:1
	s_nop 1
	v_add_f32_dpp v1, v1, v1 quad_perm:[2,3,0,1] row_mask:0xf bank_mask:0xf bound_ctrl:1
	s_nop 1
	v_add_f32_dpp v1, v1, v1 row_half_mirror row_mask:0xf bank_mask:0xf bound_ctrl:1
	s_nop 1
	v_add_f32_dpp v1, v1, v1 row_mirror row_mask:0xf bank_mask:0xf bound_ctrl:1
	v_fmamk_f32 v1, v1, 0x3c800000, v197
	v_cmp_gt_f32_e32 vcc, s81, v1
	v_mul_f32_e32 v29, 0x4b800000, v1
	s_nop 0
	v_cndmask_b32_e32 v1, v1, v29, vcc
	v_rsq_f32_e32 v1, v1
	s_nop 0
	v_mul_f32_e32 v29, 0x45800000, v1
	v_cndmask_b32_e32 v92, v1, v29, vcc
	v_pk_mul_f32 v[94:95], v[50:51], v[92:93] op_sel_hi:[1,0]
	v_pk_mul_f32 v[96:97], v[52:53], v[92:93] op_sel_hi:[1,0]
	s_waitcnt vmcnt(4)
	v_pk_fma_f32 v[94:95], v[72:73], v[94:95], v[76:77]
	v_pk_fma_f32 v[96:97], v[74:75], v[96:97], v[78:79]
	s_waitcnt vmcnt(2)
	v_pk_fma_f32 v[94:95], v[80:81], v[98:99], v[94:95] op_sel_hi:[1,0,1]
	v_pk_fma_f32 v[96:97], v[82:83], v[98:99], v[96:97] op_sel_hi:[1,0,1]
	s_waitcnt vmcnt(1)
	v_pk_mul_f32 v[94:95], v[84:85], v[94:95]
	v_pk_mul_f32 v[96:97], v[86:87], v[96:97]
	v_cvt_pk_bf16_f32 v94, v94, v95
	s_nop 0
	v_cvt_pk_bf16_f32 v95, v96, v97
	global_store_dwordx2 v[18:19], v[94:95], off offset:512
	v_lshl_add_u64 v[18:19], v[18:19], 0, s[58:59]
	s_add_u32 s8, s8, 0x800
	s_addc_u32 s9, s9, 0
	s_cmpk_eq_i32 s8, 0x2000
	s_cbranch_scc0 .LBB0_140
	v_add_u32_e32 v0, s33, v0
	s_movk_i32 s2, 0x1fff
	v_cmp_lt_i32_e32 vcc, s2, v0
	s_or_b64 s[4:5], vcc, s[4:5]
	s_andn2_b64 exec, exec, s[4:5]
	s_cbranch_execnz .LBB0_139
